# M3 tail: norm-gain vectors loaded once per unit early (after the next-unit load wait) instead of twice after the last barrier
# speedup vs baseline: 1.0085x; 1.0003x over previous
.LBB0_704:
	s_or_b64 exec, exec, s[0:1]
	v_lshl_add_u32 v71, v89, 7, s54
	s_waitcnt lgkmcnt(0)
	s_barrier
	v_lshlrev_b32_e32 v88, 2, v88
	v_and_b32_e32 v75, 0xffffffc0, v157
	v_add3_u32 v75, 0, v75, v88
	v_mad_u32_u24 v3, v89, s91, v75
	v_add_u32_e32 v46, 0x4200, v3
	ds_read_b128 v[88:91], v71
	ds_read_b128 v[92:95], v71 offset:16
	ds_read_b128 v[96:99], v71 offset:32
	ds_read_b128 v[100:103], v71 offset:48
	ds_read_b128 v[104:107], v71 offset:64
	ds_read_b128 v[108:111], v71 offset:80
	s_waitcnt lgkmcnt(4)
	v_pk_add_f32 v[90:91], v[90:91], v[94:95]
	v_pk_add_f32 v[88:89], v[88:89], v[92:93]
	v_add_f32_e32 v113, v90, v91
	v_add_f32_e32 v112, v89, v88
	ds_read_b128 v[88:91], v71 offset:96
	ds_read_b128 v[92:95], v71 offset:112
	v_add_f32_e32 v114, v112, v113
	v_fmamk_f32 v114, v114, 0x3c000000, v151
	v_rsq_f32_e32 v115, v114
	s_nop 0
	v_mul_f32_e32 v112, v56, v115
	ds_write_b32 v3, v112 offset:53248
	s_waitcnt lgkmcnt(5)
	v_pk_add_f32 v[98:99], v[98:99], v[102:103]
	v_pk_add_f32 v[96:97], v[96:97], v[100:101]
	v_add_f32_e32 v113, v98, v99
	v_add_f32_e32 v112, v97, v96
	ds_read_b128 v[96:99], v71 offset:512
	ds_read_b128 v[100:103], v71 offset:528
	v_add_f32_e32 v114, v112, v113
	v_fmamk_f32 v114, v114, 0x3c000000, v151
	v_rsq_f32_e32 v115, v114
	s_nop 0
	v_mul_f32_e32 v112, v59, v115
	ds_write_b32 v3, v112 offset:53776
	s_waitcnt lgkmcnt(6)
	v_pk_add_f32 v[106:107], v[106:107], v[110:111]
	v_pk_add_f32 v[104:105], v[104:105], v[108:109]
	v_add_f32_e32 v113, v106, v107
	v_add_f32_e32 v112, v105, v104
	ds_read_b128 v[104:107], v71 offset:544
	ds_read_b128 v[108:111], v71 offset:560
	v_add_f32_e32 v114, v112, v113
	v_fmamk_f32 v114, v114, 0x3c000000, v151
	v_rsq_f32_e32 v115, v114
	s_nop 0
	v_mul_f32_e32 v112, v58, v115
	ds_write_b32 v3, v112 offset:54304
	s_waitcnt lgkmcnt(7)
	v_pk_add_f32 v[90:91], v[90:91], v[94:95]
	v_pk_add_f32 v[88:89], v[88:89], v[92:93]
	v_add_f32_e32 v113, v90, v91
	v_add_f32_e32 v112, v89, v88
	ds_read_b128 v[88:91], v71 offset:576
	ds_read_b128 v[92:95], v71 offset:592
	v_add_f32_e32 v114, v112, v113
	v_fmamk_f32 v114, v114, 0x3c000000, v151
	v_rsq_f32_e32 v115, v114
	s_nop 0
	v_mul_f32_e32 v112, v83, v115
	ds_write_b32 v3, v112 offset:54832
	s_waitcnt lgkmcnt(7)
	v_pk_add_f32 v[98:99], v[98:99], v[102:103]
	v_pk_add_f32 v[96:97], v[96:97], v[100:101]
	v_add_f32_e32 v113, v98, v99
	v_add_f32_e32 v112, v97, v96
	ds_read_b128 v[96:99], v71 offset:608
	ds_read_b128 v[100:103], v71 offset:624
	v_add_f32_e32 v114, v112, v113
	v_fmamk_f32 v114, v114, 0x3c000000, v151
	v_rsq_f32_e32 v115, v114
	s_nop 0
	v_mul_f32_e32 v112, v52, v115
	ds_write_b32 v3, v112 offset:61696
	s_waitcnt lgkmcnt(7)
	v_pk_add_f32 v[106:107], v[106:107], v[110:111]
	v_pk_add_f32 v[104:105], v[104:105], v[108:109]
	v_add_f32_e32 v113, v106, v107
	v_add_f32_e32 v112, v105, v104
	ds_read_b128 v[104:107], v71 offset:1024
	ds_read_b128 v[108:111], v71 offset:1040
	v_add_f32_e32 v114, v112, v113
	v_fmamk_f32 v114, v114, 0x3c000000, v151
	v_rsq_f32_e32 v115, v114
	s_nop 0
	v_mul_f32_e32 v112, v77, v115
	ds_write_b32 v3, v112 offset:62224
	s_waitcnt lgkmcnt(7)
	v_pk_add_f32 v[90:91], v[90:91], v[94:95]
	v_pk_add_f32 v[88:89], v[88:89], v[92:93]
	v_add_f32_e32 v113, v90, v91
	v_add_f32_e32 v112, v89, v88
	ds_read_b128 v[88:91], v71 offset:1056
	ds_read_b128 v[92:95], v71 offset:1072
	v_add_f32_e32 v114, v112, v113
	v_fmamk_f32 v114, v114, 0x3c000000, v151
	v_rsq_f32_e32 v115, v114
	s_nop 0
	v_mul_f32_e32 v112, v53, v115
	ds_write_b32 v3, v112 offset:62752
	s_waitcnt lgkmcnt(7)
	v_pk_add_f32 v[98:99], v[98:99], v[102:103]
	v_pk_add_f32 v[96:97], v[96:97], v[100:101]
	v_add_f32_e32 v113, v98, v99
	v_add_f32_e32 v112, v97, v96
	ds_read_b128 v[96:99], v71 offset:1088
	ds_read_b128 v[100:103], v71 offset:1104
	v_add_f32_e32 v114, v112, v113
	v_fmamk_f32 v114, v114, 0x3c000000, v151
	v_rsq_f32_e32 v115, v114
	s_nop 0
	v_mul_f32_e32 v112, v54, v115
	ds_write_b32 v3, v112 offset:63280
	s_waitcnt lgkmcnt(7)
	v_pk_add_f32 v[106:107], v[106:107], v[110:111]
	v_pk_add_f32 v[104:105], v[104:105], v[108:109]
	v_add_f32_e32 v113, v106, v107
	v_add_f32_e32 v112, v105, v104
	ds_read_b128 v[104:107], v71 offset:1120
	ds_read_b128 v[108:111], v71 offset:1136
	v_add_f32_e32 v114, v112, v113
	v_fmamk_f32 v114, v114, 0x3c000000, v151
	v_rsq_f32_e32 v115, v114
	s_nop 0
	v_mul_f32_e32 v112, v48, v115
	ds_write_b32 v46, v112 offset:53248
	s_waitcnt lgkmcnt(7)
	v_pk_add_f32 v[90:91], v[90:91], v[94:95]
	v_pk_add_f32 v[88:89], v[88:89], v[92:93]
	v_add_f32_e32 v113, v90, v91
	v_add_f32_e32 v112, v89, v88
	ds_read_b128 v[88:91], v71 offset:1536
	ds_read_b128 v[92:95], v71 offset:1552
	v_add_f32_e32 v114, v112, v113
	v_fmamk_f32 v114, v114, 0x3c000000, v151
	v_rsq_f32_e32 v115, v114
	s_nop 0
	v_mul_f32_e32 v112, v73, v115
	ds_write_b32 v46, v112 offset:53776
	s_waitcnt lgkmcnt(7)
	v_pk_add_f32 v[98:99], v[98:99], v[102:103]
	v_pk_add_f32 v[96:97], v[96:97], v[100:101]
	v_add_f32_e32 v113, v98, v99
	v_add_f32_e32 v112, v97, v96
	ds_read_b128 v[96:99], v71 offset:1568
	ds_read_b128 v[100:103], v71 offset:1584
	v_add_f32_e32 v114, v112, v113
	v_fmamk_f32 v114, v114, 0x3c000000, v151
	v_rsq_f32_e32 v115, v114
	s_nop 0
	v_mul_f32_e32 v112, v49, v115
	ds_write_b32 v46, v112 offset:54304
	s_waitcnt lgkmcnt(7)
	v_pk_add_f32 v[106:107], v[106:107], v[110:111]
	v_pk_add_f32 v[104:105], v[104:105], v[108:109]
	v_add_f32_e32 v113, v106, v107
	v_add_f32_e32 v112, v105, v104
	ds_read_b128 v[104:107], v71 offset:1600
	ds_read_b128 v[108:111], v71 offset:1616
	v_add_f32_e32 v114, v112, v113
	v_fmamk_f32 v114, v114, 0x3c000000, v151
	v_rsq_f32_e32 v115, v114
	s_nop 0
	v_mul_f32_e32 v112, v50, v115
	ds_write_b32 v46, v112 offset:54832
	s_waitcnt lgkmcnt(7)
	v_pk_add_f32 v[90:91], v[90:91], v[94:95]
	v_pk_add_f32 v[88:89], v[88:89], v[92:93]
	v_add_f32_e32 v113, v90, v91
	v_add_f32_e32 v112, v89, v88
	ds_read_b128 v[88:91], v71 offset:1632
	ds_read_b128 v[92:95], v71 offset:1648
	v_add_f32_e32 v114, v112, v113
	v_fmamk_f32 v114, v114, 0x3c000000, v151
	v_rsq_f32_e32 v115, v114
	s_nop 0
	v_mul_f32_e32 v112, v51, v115
	ds_write_b32 v46, v112 offset:61696
	s_waitcnt lgkmcnt(7)
	v_pk_add_f32 v[98:99], v[98:99], v[102:103]
	v_pk_add_f32 v[96:97], v[96:97], v[100:101]
	v_add_f32_e32 v113, v98, v99
	v_add_f32_e32 v112, v97, v96
	v_add_f32_e32 v114, v112, v113
	v_fmamk_f32 v114, v114, 0x3c000000, v151
	v_rsq_f32_e32 v115, v114
	s_nop 0
	v_mul_f32_e32 v112, v68, v115
	ds_write_b32 v46, v112 offset:62224
	s_waitcnt lgkmcnt(5)
	v_pk_add_f32 v[106:107], v[106:107], v[110:111]
	v_pk_add_f32 v[104:105], v[104:105], v[108:109]
	v_add_f32_e32 v113, v106, v107
	v_add_f32_e32 v112, v105, v104
	v_add_f32_e32 v114, v112, v113
	v_fmamk_f32 v114, v114, 0x3c000000, v151
	v_rsq_f32_e32 v115, v114
	s_nop 0
	v_mul_f32_e32 v112, v45, v115
	ds_write_b32 v46, v112 offset:62752
	s_waitcnt lgkmcnt(3)
	v_pk_add_f32 v[90:91], v[90:91], v[94:95]
	v_pk_add_f32 v[88:89], v[88:89], v[92:93]
	v_add_f32_e32 v113, v90, v91
	v_add_f32_e32 v112, v89, v88
	v_add_f32_e32 v114, v112, v113
	v_fmamk_f32 v114, v114, 0x3c000000, v151
	v_rsq_f32_e32 v115, v114
	s_nop 0
	v_mul_f32_e32 v112, v44, v115
	ds_write_b32 v46, v112 offset:63280
	s_add_u32 s0, s36, s58
	v_readlane_b32 s56, v246, 4
	s_addc_u32 s1, s37, 0
	v_readlane_b32 s68, v246, 16
	v_readlane_b32 s69, v246, 17
	s_add_u32 s2, s68, s4
	s_addc_u32 s3, s69, 0
	s_waitcnt vmcnt(1)
	v_lshlrev_b32_e32 v75, 16, v67
	s_waitcnt vmcnt(0)
	v_lshlrev_b32_e32 v208, 2, v156
	global_load_dwordx4 v[200:203], v208, s[2:3]
	global_load_dwordx4 v[204:207], v208, s[2:3] offset:16
	v_and_b32_e32 v108, 0xffff0000, v60
	v_lshlrev_b32_e32 v109, 16, v61
	v_and_b32_e32 v113, 0xffff0000, v61
	v_lshlrev_b32_e32 v114, 16, v62
	v_and_b32_e32 v62, 0xffff0000, v62
	v_mov_b64_e32 v[106:107], v[22:23]
	v_mov_b64_e32 v[102:103], v[18:19]
	v_lshlrev_b32_e32 v115, 16, v63
	v_and_b32_e32 v63, 0xffff0000, v63
	v_lshl_add_u64 v[144:145], v[144:145], 0, s[16:17]
	v_mov_b32_e32 v112, v154
	v_mov_b32_e32 v111, v129
	v_mov_b64_e32 v[98:99], v[14:15]
	v_mov_b64_e32 v[104:105], v[20:21]
	v_mov_b64_e32 v[100:101], v[16:17]
	v_mov_b64_e32 v[96:97], v[12:13]
	v_mov_b32_e32 v110, v1
	s_add_i32 s38, s38, s39
	s_add_i32 s40, s40, s41
	v_mov_b32_e32 v158, v155
	v_readlane_b32 s57, v246, 5
	v_readlane_b32 s58, v246, 6
	v_readlane_b32 s59, v246, 7
	v_readlane_b32 s60, v246, 8
	v_readlane_b32 s61, v246, 9
	v_readlane_b32 s62, v246, 10
	v_readlane_b32 s63, v246, 11
	v_readlane_b32 s64, v246, 12
	v_readlane_b32 s65, v246, 13
	v_mov_b32_e32 v83, v0
	v_mov_b64_e32 v[94:95], v[10:11]
	v_mov_b64_e32 v[92:93], v[8:9]
	v_readlane_b32 s66, v246, 14
	v_readlane_b32 s67, v246, 15
	v_readlane_b32 s70, v246, 18
	v_readlane_b32 s71, v246, 19
	s_nop 0
	s_nop 0
	s_nop 0
	s_nop 1
	s_nop 0
	s_nop 0
	v_and_b32_e32 v76, 0xffff0000, v67
	s_nop 1
	s_nop 0
	v_mov_b64_e32 v[90:91], v[6:7]
	v_mov_b64_e32 v[88:89], v[4:5]
	s_nop 0
	s_nop 0
	s_nop 0
	s_nop 1
	s_nop 0
	s_nop 0
	v_lshlrev_b32_e32 v72, 16, v65
	v_and_b32_e32 v65, 0xffff0000, v65
	s_nop 0
	v_lshlrev_b32_e32 v73, 16, v66
	s_nop 0
	v_and_b32_e32 v74, 0xffff0000, v66
	v_lshl_add_u64 v[66:67], s[0:1], 0, v[82:83]
	s_nop 0
	s_nop 0
	s_nop 0
	s_nop 1
	v_lshlrev_b32_e32 v70, 2, v156
	v_and_b32_e32 v71, 0xffff0000, v64
	v_lshlrev_b64 v[58:59], 11, v[84:85]
	s_nop 1
	s_nop 0
	s_nop 0
	s_nop 0
	s_nop 1
	s_nop 0
	v_lshl_add_u64 v[68:69], v[66:67], 0, v[58:59]
	s_nop 0
	s_nop 1
	s_nop 0
	s_nop 0
	s_nop 0
	s_nop 1
	s_nop 0
	s_waitcnt lgkmcnt(0)
	s_barrier
	s_waitcnt vmcnt(0)
	v_mov_b32_e32 v44, v200
	v_mov_b32_e32 v45, v201
	v_mov_b32_e32 v46, v202
	v_mov_b32_e32 v47, v203
	v_mov_b32_e32 v48, v204
	v_mov_b32_e32 v49, v205
	v_mov_b32_e32 v50, v206
	v_mov_b32_e32 v51, v207
	v_lshlrev_b32_e32 v3, 16, v64
	v_add_u32_e32 v64, 0, v70
	v_mad_u64_u32 v[56:57], s[12:13], v86, s95, v[64:65]
	ds_read_b128 v[52:55], v56 offset:53248
	ds_read_b128 v[56:59], v56 offset:53264
	v_mov_b64_e32 v[86:87], v[42:43]
	v_mov_b64_e32 v[84:85], v[40:41]
	s_andn2_b64 vcc, exec, s[24:25]
	s_waitcnt vmcnt(1) lgkmcnt(1)
	v_mul_f32_e32 v44, v52, v44
	v_mul_f32_e32 v45, v53, v45
	v_mul_f32_e32 v46, v54, v46
	v_mul_f32_e32 v47, v55, v47
	s_waitcnt vmcnt(0) lgkmcnt(0)
	v_mul_f32_e32 v48, v56, v48
	v_mul_f32_e32 v49, v57, v49
	v_mul_f32_e32 v50, v58, v50
	v_mul_f32_e32 v51, v59, v51
	v_mul_f32_e32 v3, v44, v3
	v_mul_f32_e32 v44, v45, v71
	v_mul_f32_e32 v45, v46, v72
	v_mul_f32_e32 v46, v47, v65
	v_mul_f32_e32 v47, v48, v73
	v_mul_f32_e32 v48, v49, v74
	v_mul_f32_e32 v49, v50, v75
	v_mul_f32_e32 v50, v51, v76
	v_cvt_pk_bf16_f32 v44, v3, v44
	v_cvt_pk_bf16_f32 v45, v45, v46
	v_cvt_pk_bf16_f32 v46, v47, v48
	v_cvt_pk_bf16_f32 v47, v49, v50
	global_store_dwordx4 v[68:69], v[44:47], off
	s_nop 1
	v_mov_b32_e32 v44, v200
	v_mov_b32_e32 v45, v201
	v_mov_b32_e32 v46, v202
	v_mov_b32_e32 v47, v203
	s_nop 0
	v_mov_b32_e32 v48, v204
	v_mov_b32_e32 v49, v205
	v_mov_b32_e32 v50, v206
	v_mov_b32_e32 v51, v207
	v_lshlrev_b32_e32 v65, 16, v60
	v_lshlrev_b64 v[52:53], 11, v[80:81]
	v_mad_u64_u32 v[2:3], s[0:1], v2, s95, v[64:65]
	v_lshl_add_u64 v[60:61], v[66:67], 0, v[52:53]
	ds_read_b128 v[52:55], v2 offset:53248
	ds_read_b128 v[56:59], v2 offset:53264
	v_mov_b64_e32 v[82:83], v[38:39]
	v_mov_b64_e32 v[74:75], v[34:35]
	v_mov_b64_e32 v[78:79], v[30:31]
	v_mov_b64_e32 v[70:71], v[26:27]
	v_mov_b64_e32 v[80:81], v[36:37]
	v_mov_b64_e32 v[72:73], v[32:33]
	v_mov_b64_e32 v[76:77], v[28:29]
	v_mov_b64_e32 v[68:69], v[24:25]
	s_waitcnt lgkmcnt(1)
	v_mul_f32_e32 v2, v52, v44
	v_mul_f32_e32 v3, v53, v45
	v_mul_f32_e32 v44, v54, v46
	v_mul_f32_e32 v45, v55, v47
	s_waitcnt lgkmcnt(0)
	v_mul_f32_e32 v46, v56, v48
	v_mul_f32_e32 v47, v57, v49
	v_mul_f32_e32 v48, v58, v50
	v_mul_f32_e32 v49, v59, v51
	v_mul_f32_e32 v45, v45, v113
	v_mul_f32_e32 v46, v46, v114
	v_mul_f32_e32 v47, v47, v62
	v_mul_f32_e32 v2, v2, v65
	v_mul_f32_e32 v3, v3, v108
	v_mul_f32_e32 v50, v44, v109
	v_mul_f32_e32 v48, v48, v115
	v_mul_f32_e32 v49, v49, v63
	v_cvt_pk_bf16_f32 v44, v2, v3
	v_cvt_pk_bf16_f32 v45, v50, v45
	v_cvt_pk_bf16_f32 v46, v46, v47
	v_cvt_pk_bf16_f32 v47, v48, v49
	global_store_dwordx4 v[60:61], v[44:47], off
	s_cbranch_vccz .LBB0_743
